# v19 + nt hint also on x-conversion, gather and retention-scores tile loads (all read once)
# baseline (speedup 1.0000x reference)
.Lxcv4_top:
	v_add_u32_e32 v7, s11, v6
	v_cmp_gt_i32_e32 vcc, s16, v7
	s_and_b64 exec, s[14:15], vcc
	s_cbranch_execz .Lxcv4_done
	v_ashrrev_i32_e32 v5, 31, v4
	v_lshl_add_u64 v[46:47], v[4:5], 4, s[12:13]
	v_lshl_add_u64 v[48:49], v[46:47], 0, s[18:19]
	v_lshl_add_u64 v[50:51], v[48:49], 0, s[18:19]
	v_lshl_add_u64 v[52:53], v[50:51], 0, s[18:19]
	global_load_dwordx4 v[8:11], v[46:47], off nt
	global_load_dwordx4 v[12:15], v[46:47], off offset:16 nt
	global_load_dwordx4 v[16:19], v[48:49], off nt
	global_load_dwordx4 v[20:23], v[48:49], off offset:16 nt
	global_load_dwordx4 v[24:27], v[50:51], off nt
	global_load_dwordx4 v[28:31], v[50:51], off offset:16 nt
	global_load_dwordx4 v[32:35], v[52:53], off nt
	global_load_dwordx4 v[36:39], v[52:53], off offset:16 nt
	v_add_u32_e32 v6, s17, v6
	v_add_u32_e32 v4, s20, v4
	s_waitcnt vmcnt(6)
	v_cvt_pk_bf16_f32 v8, v8, v9
	v_cvt_pk_bf16_f32 v9, v10, v11
	v_cvt_pk_bf16_f32 v10, v12, v13
	v_cvt_pk_bf16_f32 v11, v14, v15
	global_store_dwordx4 v[2:3], v[8:11], off
	v_lshl_add_u64 v[2:3], v[2:3], 0, s[6:7]
	s_waitcnt vmcnt(5)
	v_cvt_pk_bf16_f32 v16, v16, v17
	v_cvt_pk_bf16_f32 v17, v18, v19
	v_cvt_pk_bf16_f32 v18, v20, v21
	v_cvt_pk_bf16_f32 v19, v22, v23
	global_store_dwordx4 v[2:3], v[16:19], off
	v_lshl_add_u64 v[2:3], v[2:3], 0, s[6:7]
	s_waitcnt vmcnt(4)
	v_cvt_pk_bf16_f32 v24, v24, v25
	v_cvt_pk_bf16_f32 v25, v26, v27
	v_cvt_pk_bf16_f32 v26, v28, v29
	v_cvt_pk_bf16_f32 v27, v30, v31
	global_store_dwordx4 v[2:3], v[24:27], off
	v_lshl_add_u64 v[2:3], v[2:3], 0, s[6:7]
	s_waitcnt vmcnt(3)
	v_cvt_pk_bf16_f32 v32, v32, v33
	v_cvt_pk_bf16_f32 v33, v34, v35
	v_cvt_pk_bf16_f32 v34, v36, v37
	v_cvt_pk_bf16_f32 v35, v38, v39
	global_store_dwordx4 v[2:3], v[32:35], off
	v_lshl_add_u64 v[2:3], v[2:3], 0, s[6:7]
	s_branch .Lxcv4_top

.LBB0_80:
	v_ashrrev_i32_e32 v5, 31, v4
	v_lshl_add_u64 v[12:13], v[4:5], 4, s[12:13]
	global_load_dwordx4 v[8:11], v[12:13], off nt
	s_nop 0
	global_load_dwordx4 v[12:15], v[12:13], off offset:16 nt
	v_add_u32_e32 v6, s4, v6
	v_cmp_lt_i32_e32 vcc, s10, v6
	v_add_u32_e32 v4, s5, v4
	s_or_b64 s[8:9], vcc, s[8:9]
	s_waitcnt vmcnt(1)
	v_cvt_pk_bf16_f32 v8, v8, v9
	v_cvt_pk_bf16_f32 v9, v10, v11
	s_waitcnt vmcnt(0)
	v_cvt_pk_bf16_f32 v10, v12, v13
	v_cvt_pk_bf16_f32 v11, v14, v15
	global_store_dwordx4 v[2:3], v[8:11], off
	v_lshl_add_u64 v[2:3], v[2:3], 0, s[6:7]
	s_andn2_b64 exec, exec, s[8:9]
	s_cbranch_execnz .LBB0_80

.LBB0_266:
	s_or_b64 exec, exec, s[0:1]
	v_readlane_b32 s0, v234, 0
	s_cmpk_lt_i32 s0, 0x400
	s_mov_b32 s94, s77
	s_cselect_b64 s[76:77], -1, 0
	v_mov_b32_e32 v36, v161
	s_waitcnt lgkmcnt(0)
	s_barrier
	s_and_b64 vcc, exec, s[76:77]
	v_readfirstlane_b32 s0, v36
	v_readlane_b32 s1, v234, 1
	s_cbranch_vccz .LBB0_271
	v_readlane_b32 s1, v234, 39
	s_and_b32 s1, s1, 0x600
	s_add_u32 s4, s58, s1
	v_readlane_b32 s12, v234, 0
	s_addc_u32 s5, s59, 0
	s_ashr_i32 s8, s12, 8
	s_ashr_i32 s9, s8, 31
	s_lshl_b32 s1, s12, 6
	s_lshl_b64 s[8:9], s[8:9], 12
	s_and_b32 s1, s1, 0xfc0
	v_ashrrev_i32_e32 v32, 5, v36
	s_or_b32 s8, s8, s1
	v_ashrrev_i32_e32 v33, 31, v32
	v_lshl_add_u64 v[0:1], s[8:9], 0, v[32:33]
	v_lshlrev_b32_e32 v2, 3, v36
	v_lshlrev_b64 v[0:1], 12, v[0:1]
	v_and_b32_e32 v52, 0xf8, v2
	v_lshl_add_u64 v[0:1], s[4:5], 0, v[0:1]
	v_mov_b32_e32 v35, 0
	v_lshlrev_b32_e32 v34, 1, v52
	v_lshl_add_u64 v[24:25], v[0:1], 0, v[34:35]
	s_mov_b32 s3, 0x10000
	v_add_co_u32_e32 v12, vcc, s3, v24
	s_mov_b32 s14, 0x20000
	s_nop 0
	v_addc_co_u32_e32 v13, vcc, 0, v25, vcc
	v_add_co_u32_e32 v20, vcc, s14, v24
	s_mov_b32 s15, 0x30000
	s_nop 0
	v_addc_co_u32_e32 v21, vcc, 0, v25, vcc
	v_add_co_u32_e32 v28, vcc, s15, v24
	global_load_dwordx4 v[0:3], v[24:25], off nt
	global_load_dwordx4 v[4:7], v[24:25], off offset:2048 nt
	v_addc_co_u32_e32 v29, vcc, 0, v25, vcc
	global_load_dwordx4 v[8:11], v[12:13], off nt
	s_nop 0
	global_load_dwordx4 v[12:15], v[12:13], off offset:2048 nt
	s_nop 0
	global_load_dwordx4 v[16:19], v[20:21], off nt
	s_nop 0
	global_load_dwordx4 v[20:23], v[20:21], off offset:2048 nt
	s_nop 0
	global_load_dwordx4 v[24:27], v[28:29], off nt
	s_nop 0
	global_load_dwordx4 v[28:31], v[28:29], off offset:2048 nt
	v_lshlrev_b32_e32 v34, 4, v36
	s_ashr_i32 s4, s0, 3
	v_and_b32_e32 v38, 15, v36
	v_and_b32_e32 v34, 0x1f0, v34
	s_lshr_b32 s1, s0, 2
	s_and_b32 s5, s4, -16
	s_andn2_b32 s4, s4, 31
	v_bfe_u32 v37, v36, 4, 2
	v_add_u32_e32 v53, 0, v34
	v_and_or_b32 v34, s1, 48, v38
	s_movk_i32 s1, 0x210
	v_or_b32_e32 v36, s4, v38
	v_mul_lo_u32 v36, v36, s1
	v_add_u32_e32 v56, 0, v36
	v_lshlrev_b32_e32 v36, 2, v37
	v_lshlrev_b32_e32 v55, 4, v37
	v_or_b32_e32 v37, s5, v36
	v_or_b32_e32 v40, 16, v37
	v_or_b32_e32 v36, s4, v36
	v_sub_u32_e32 v39, v34, v40
	v_sub_u32_e32 v41, 63, v40
	v_or_b32_e32 v43, 1, v36
	v_cvt_f32_i32_e32 v39, v39
	v_cvt_f32_i32_e32 v41, v41
	v_sub_u32_e32 v44, v34, v43
	v_sub_u32_e32 v43, 63, v43
	v_cvt_f32_i32_e32 v45, v43
	v_or_b32_e32 v43, 2, v36
	v_or3_b32 v42, v38, s5, 16
	v_sub_u32_e32 v46, v34, v43
	v_sub_u32_e32 v43, 63, v43
	v_mul_lo_u32 v42, v42, s1
	v_cvt_f32_i32_e32 v44, v44
	v_cvt_f32_i32_e32 v46, v46
	v_cvt_f32_i32_e32 v47, v43
	v_add_u32_e32 v57, 0, v42
	v_sub_f32_e64 v42, |v39|, v41
	v_sub_u32_e32 v39, v34, v36
	v_sub_u32_e32 v41, 63, v36
	v_cvt_f32_i32_e32 v39, v39
	v_cvt_f32_i32_e32 v41, v41
	v_sub_f32_e64 v44, |v44|, v45
	v_sub_f32_e64 v45, |v46|, v47
	v_or_b32_e32 v46, 17, v37
	v_sub_u32_e32 v47, v34, v46
	v_sub_u32_e32 v46, 63, v46
	v_sub_f32_e64 v43, |v39|, v41
	v_or_b32_e32 v39, 3, v36
	v_cvt_f32_i32_e32 v48, v46
	v_or_b32_e32 v46, 18, v37
	v_or_b32_e32 v37, 19, v37
	v_mad_u32_u24 v54, v34, s1, 0
	v_sub_u32_e32 v41, v34, v39
	v_sub_u32_e32 v49, v34, v46
	v_sub_u32_e32 v46, 63, v46
	v_sub_u32_e32 v34, v34, v37
	v_sub_u32_e32 v37, 63, v37
	v_cvt_f32_i32_e32 v47, v47
	v_cvt_f32_i32_e32 v49, v49
	v_cvt_f32_i32_e32 v50, v46
	v_cvt_f32_i32_e32 v34, v34
	v_cvt_f32_i32_e32 v37, v37
	v_readlane_b32 s13, v234, 1
	v_sub_u32_e32 v39, 63, v39
	v_cvt_f32_i32_e32 v41, v41
	v_cvt_f32_i32_e32 v39, v39
	s_ashr_i32 s13, s12, 31
	s_lshl_b32 s0, s0, 5
	s_lshl_b64 s[4:5], s[12:13], 13
	s_and_b32 s0, s0, 0x1800
	v_sub_f32_e64 v47, |v47|, v48
	v_sub_f32_e64 v48, |v49|, v50
	v_sub_f32_e64 v49, |v34|, v37
	v_lshl_or_b32 v34, v38, 7, s0
	s_add_u32 s0, s84, s4
	v_mul_lo_u32 v58, v32, s1
	s_addc_u32 s1, s85, s5
	v_sub_f32_e64 v46, |v41|, v39
	v_lshl_add_u64 v[38:39], s[0:1], 0, v[34:35]
	s_add_i32 s0, s12, s82
	v_ashrrev_i32_e32 v41, 31, v40
	v_ashrrev_i32_e32 v37, 31, v36
	v_mov_b64_e32 v[50:51], 0x30400000
	s_lshl_b32 s20, s0, 6
	s_lshl_b32 s22, s0, 2
	s_mov_b32 s0, s12
	s_mov_b32 s7, 0
	v_lshl_add_u64 v[36:37], v[36:37], 1, v[50:51]
	s_lshl_b64 s[8:9], s[60:61], 13
	v_lshl_add_u64 v[40:41], v[40:41], 1, v[50:51]
	s_lshl_b32 s21, s82, 6
	s_lshl_b32 s23, s82, 2
	s_mov_b32 s24, 0xc2fc0000
	v_add_u32_e32 v50, v53, v58
	v_lshlrev_b32_e32 v34, 1, v52
	s_mov_b32 s25, 0x800000
	v_add_u32_e32 v51, v54, v55
	v_add_u32_e32 v52, v56, v55
	v_add_u32_e32 v53, v57, v55
	v_mov_b32_e32 v54, 0x42800000
	v_mov_b32_e32 v55, 0x42000000
	v_not_b32_e32 v56, 63
	v_writelane_b32 v234, s0, 0
	s_mov_b32 s26, s12
	s_nop 0
	v_writelane_b32 v234, s1, 1
	s_branch .LBB0_269

.LBB0_269:
	s_bfe_u32 s0, s26, 0x20006
	v_cvt_f32_ubyte0_e32 v57, s0
	v_sub_f32_e32 v57, 0xc0a00000, v57
	v_cmp_gt_f32_e64 s[4:5], s24, v57
	s_and_b64 s[0:1], s[4:5], exec
	s_cselect_b32 s0, 0xffffffc0, 0
	s_add_i32 s26, s26, s82
	s_cmpk_gt_i32 s26, 0x3ff
	s_cselect_b64 s[12:13], -1, 0
	s_and_b64 vcc, exec, s[12:13]
	s_barrier
	s_waitcnt vmcnt(7)
	ds_write_b128 v50, v[0:3]
	s_waitcnt vmcnt(6)
	ds_write_b128 v50, v[4:7] offset:33792
	s_waitcnt vmcnt(5)
	ds_write_b128 v50, v[8:11] offset:8448
	s_waitcnt vmcnt(4)
	ds_write_b128 v50, v[12:15] offset:42240
	s_waitcnt vmcnt(3)
	ds_write_b128 v50, v[16:19] offset:16896
	s_waitcnt vmcnt(2)
	ds_write_b128 v50, v[20:23] offset:50688
	s_waitcnt vmcnt(1)
	ds_write_b128 v50, v[24:27] offset:25344
	s_waitcnt vmcnt(0)
	ds_write_b128 v50, v[28:31] offset:59136
	s_cbranch_vccnz .LBB0_268
	s_ashr_i32 s28, s26, 8
	s_ashr_i32 s29, s28, 31
	s_and_b32 s6, s20, 0xfc0
	s_lshl_b64 s[28:29], s[28:29], 24
	v_lshl_add_u64 v[0:1], s[6:7], 0, v[32:33]
	s_add_u32 s28, s58, s28
	v_lshlrev_b64 v[0:1], 12, v[0:1]
	s_addc_u32 s29, s59, s29
	s_and_b32 s1, s22, 0x300
	v_lshl_add_u64 v[0:1], s[28:29], 0, v[0:1]
	s_lshl_b32 s6, s1, 1
	v_lshl_add_u64 v[0:1], v[0:1], 0, s[6:7]
	v_lshl_add_u64 v[24:25], v[0:1], 0, v[34:35]
	v_add_co_u32_e32 v12, vcc, s3, v24
	global_load_dwordx4 v[0:3], v[24:25], off nt
	global_load_dwordx4 v[4:7], v[24:25], off offset:2048 nt
	v_addc_co_u32_e32 v13, vcc, 0, v25, vcc
	v_add_co_u32_e32 v20, vcc, s14, v24
	global_load_dwordx4 v[8:11], v[12:13], off nt
	s_nop 0
	global_load_dwordx4 v[12:15], v[12:13], off offset:2048 nt
	v_addc_co_u32_e32 v21, vcc, 0, v25, vcc
	v_add_co_u32_e32 v28, vcc, s15, v24
	global_load_dwordx4 v[16:19], v[20:21], off nt
	s_nop 0
	global_load_dwordx4 v[20:23], v[20:21], off offset:2048 nt
	v_addc_co_u32_e32 v29, vcc, 0, v25, vcc
	global_load_dwordx4 v[24:27], v[28:29], off nt
	s_nop 0
	global_load_dwordx4 v[28:31], v[28:29], off offset:2048 nt
	s_branch .LBB0_268

.Lgat4_top:
	s_add_i32 s18, s13, s16
	s_cmpk_lt_i32 s18, 0x4000
	s_cbranch_scc0 .Lgat4_done
	s_ashr_i32 s9, s8, 31
	s_lshl_b64 s[10:11], s[8:9], 2
	s_add_u32 s10, s6, s10
	s_addc_u32 s11, s7, s11
	s_add_u32 s20, s10, s17
	s_addc_u32 s21, s11, 0
	s_add_u32 s22, s20, s17
	s_addc_u32 s23, s21, 0
	s_add_u32 s24, s22, s17
	s_addc_u32 s25, s23, 0
	v_lshl_add_u64 v[42:43], v[0:1], 0, s[4:5]
	v_lshl_add_u64 v[44:45], v[42:43], 0, s[4:5]
	v_lshl_add_u64 v[46:47], v[44:45], 0, s[4:5]
	global_load_dwordx4 v[4:7], v8, s[10:11]
	global_load_dwordx4 v[18:21], v8, s[20:21]
	global_load_dwordx4 v[22:25], v8, s[22:23]
	global_load_dwordx4 v[26:29], v8, s[24:25]
	global_load_dwordx4 v[10:13], v[0:1], off nt
	global_load_dwordx4 v[30:33], v[42:43], off nt
	global_load_dwordx4 v[34:37], v[44:45], off nt
	global_load_dwordx4 v[38:41], v[46:47], off nt
	s_waitcnt vmcnt(4)
	v_lshlrev_b32_e32 v4, 2, v4
	v_lshlrev_b32_e32 v6, 2, v6
	ds_read_b32 v6, v6
	ds_read_b32 v4, v4
	v_lshlrev_b32_e32 v18, 2, v18
	v_lshlrev_b32_e32 v20, 2, v20
	ds_read_b32 v20, v20
	ds_read_b32 v18, v18
	v_lshlrev_b32_e32 v22, 2, v22
	v_lshlrev_b32_e32 v24, 2, v24
	ds_read_b32 v24, v24
	ds_read_b32 v22, v22
	v_lshlrev_b32_e32 v26, 2, v26
	v_lshlrev_b32_e32 v28, 2, v28
	ds_read_b32 v28, v28
	ds_read_b32 v26, v26
	s_waitcnt lgkmcnt(0)
	v_add_u32_e32 v6, v6, v7
	v_add_u32_e32 v4, v4, v5
	v_add_u32_e32 v20, v20, v21
	v_add_u32_e32 v18, v18, v19
	v_add_u32_e32 v24, v24, v25
	v_add_u32_e32 v22, v22, v23
	v_add_u32_e32 v28, v28, v29
	v_add_u32_e32 v26, v26, v27
	s_waitcnt vmcnt(0)
	v_ashrrev_i32_e32 v5, 31, v4
	v_ashrrev_i32_e32 v7, 31, v6
	v_lshlrev_b64 v[14:15], 10, v[4:5]
	v_lshlrev_b64 v[16:17], 10, v[6:7]
	v_lshl_add_u64 v[14:15], v[2:3], 0, v[14:15]
	v_lshl_add_u64 v[16:17], v[2:3], 0, v[16:17]
	global_store_dwordx4 v[14:15], v[10:13], off
	global_store_dwordx4 v[16:17], v[10:13], off
	s_ashr_i32 s1, s0, 31
	s_lshl_b64 s[14:15], s[0:1], 2
	s_add_u32 s14, s50, s14
	s_addc_u32 s15, s51, s15
	v_mov_b32_e32 v5, v6
	s_and_saveexec_b64 s[26:27], vcc
	global_store_dwordx2 v8, v[4:5], s[14:15]
	s_or_b64 exec, exec, s[26:27]
	s_add_i32 s0, s0, s3
	s_add_i32 s8, s8, s12
	s_add_i32 s13, s13, s80
	v_ashrrev_i32_e32 v19, 31, v18
	v_ashrrev_i32_e32 v21, 31, v20
	v_lshlrev_b64 v[14:15], 10, v[18:19]
	v_lshlrev_b64 v[16:17], 10, v[20:21]
	v_lshl_add_u64 v[14:15], v[2:3], 0, v[14:15]
	v_lshl_add_u64 v[16:17], v[2:3], 0, v[16:17]
	global_store_dwordx4 v[14:15], v[30:33], off
	global_store_dwordx4 v[16:17], v[30:33], off
	s_ashr_i32 s1, s0, 31
	s_lshl_b64 s[14:15], s[0:1], 2
	s_add_u32 s14, s50, s14
	s_addc_u32 s15, s51, s15
	v_mov_b32_e32 v19, v20
	s_and_saveexec_b64 s[26:27], vcc
	global_store_dwordx2 v8, v[18:19], s[14:15]
	s_or_b64 exec, exec, s[26:27]
	s_add_i32 s0, s0, s3
	s_add_i32 s8, s8, s12
	s_add_i32 s13, s13, s80
	v_ashrrev_i32_e32 v23, 31, v22
	v_ashrrev_i32_e32 v25, 31, v24
	v_lshlrev_b64 v[14:15], 10, v[22:23]
	v_lshlrev_b64 v[16:17], 10, v[24:25]
	v_lshl_add_u64 v[14:15], v[2:3], 0, v[14:15]
	v_lshl_add_u64 v[16:17], v[2:3], 0, v[16:17]
	global_store_dwordx4 v[14:15], v[34:37], off
	global_store_dwordx4 v[16:17], v[34:37], off
	s_ashr_i32 s1, s0, 31
	s_lshl_b64 s[14:15], s[0:1], 2
	s_add_u32 s14, s50, s14
	s_addc_u32 s15, s51, s15
	v_mov_b32_e32 v23, v24
	s_and_saveexec_b64 s[26:27], vcc
	global_store_dwordx2 v8, v[22:23], s[14:15]
	s_or_b64 exec, exec, s[26:27]
	s_add_i32 s0, s0, s3
	s_add_i32 s8, s8, s12
	s_add_i32 s13, s13, s80
	v_ashrrev_i32_e32 v27, 31, v26
	v_ashrrev_i32_e32 v29, 31, v28
	v_lshlrev_b64 v[14:15], 10, v[26:27]
	v_lshlrev_b64 v[16:17], 10, v[28:29]
	v_lshl_add_u64 v[14:15], v[2:3], 0, v[14:15]
	v_lshl_add_u64 v[16:17], v[2:3], 0, v[16:17]
	global_store_dwordx4 v[14:15], v[38:41], off
	global_store_dwordx4 v[16:17], v[38:41], off
	s_ashr_i32 s1, s0, 31
	s_lshl_b64 s[14:15], s[0:1], 2
	s_add_u32 s14, s50, s14
	s_addc_u32 s15, s51, s15
	v_mov_b32_e32 v27, v28
	s_and_saveexec_b64 s[26:27], vcc
	global_store_dwordx2 v8, v[26:27], s[14:15]
	s_or_b64 exec, exec, s[26:27]
	s_add_i32 s0, s0, s3
	s_add_i32 s8, s8, s12
	s_add_i32 s13, s13, s80
	v_lshl_add_u64 v[0:1], v[46:47], 0, s[4:5]
	s_branch .Lgat4_top

.LBB0_1202:
	s_ashr_i32 s9, s8, 31
	s_lshl_b64 s[10:11], s[8:9], 2
	s_add_u32 s10, s6, s10
	s_addc_u32 s11, s7, s11
	global_load_dwordx4 v[4:7], v8, s[10:11]
	global_load_dwordx4 v[10:13], v[0:1], off nt
	s_waitcnt vmcnt(1)
	v_lshlrev_b32_e32 v4, 2, v4
	v_lshlrev_b32_e32 v6, 2, v6
	v_add_u32_e32 v4, 0, v4
	v_add_u32_e32 v6, 0, v6
	ds_read_b32 v6, v6
	ds_read_b32 v4, v4
	s_waitcnt lgkmcnt(1)
	v_add_u32_e32 v6, v6, v7
	s_waitcnt lgkmcnt(0)
	v_add_u32_e32 v4, v4, v5
	v_ashrrev_i32_e32 v5, 31, v4
	v_ashrrev_i32_e32 v7, 31, v6
	v_lshlrev_b64 v[14:15], 10, v[4:5]
	v_lshlrev_b64 v[16:17], 10, v[6:7]
	v_lshl_add_u64 v[14:15], v[2:3], 0, v[14:15]
	v_lshl_add_u64 v[16:17], v[2:3], 0, v[16:17]
	s_waitcnt vmcnt(0)
	global_store_dwordx4 v[14:15], v[10:13], off
	global_store_dwordx4 v[16:17], v[10:13], off
	s_and_saveexec_b64 s[10:11], vcc
	s_cbranch_execz .LBB0_1201
	s_ashr_i32 s1, s0, 31
	s_lshl_b64 s[14:15], s[0:1], 2
	s_add_u32 s14, s50, s14
	v_mov_b32_e32 v5, v6
	s_addc_u32 s15, s51, s15
	global_store_dwordx2 v8, v[4:5], s[14:15]
	s_branch .LBB0_1201
